# MLA loop: additionally rebalance softmax VALU across QK^T MFMA gaps
# baseline (speedup 1.0000x reference)
; #define SBAR() __builtin_amdgcn_sched_barrier(0)
; #define SLOAD(i, k0) do { sr_[i].vs0 = *reinterpret_cast<const bf16x8*>(vptr + (size_t)((k0) + sr) * vstr); \
;     sr_[i].vs1 = *reinterpret_cast<const bf16x8*>(vptr + (size_t)((k0) + 32 + sr) * vstr); \
;     sr_[i].ks0 = *reinterpret_cast<const bf16x8*>(kptr + (size_t)((k0) + sr) * kstr); \
;     sr_[i].ks1 = *reinterpret_cast<const bf16x8*>(kptr + (size_t)((k0) + 32 + sr) * kstr); } while (0)
; template <int NDQ, int NDV> ...
;     ...
;     SBAR(); qkt<NDQ>(pB0, pB1, K_lds + SHM_K, qr, r32, hi);
;     finishSM(pA0, pA1, alA, l_reg, pa0, pa1, pa2, pa3); SBAR();
;     SLOAD(SO, (j + 2) * 64); SBAR();
;     pv_d0<NDV>(o, vb0, pa0, pa1, pa2, pa3); partialSM(pB0, pB1, m_reg, mnB, alB, Cs, thr);
.LBB0_1488:
	ds_read_b128 v[32:35], v175 offset:49152
	ds_read_b128 v[36:39], v175 offset:57344
	ds_read_b128 v[192:195], v176 offset:49152
	ds_read_b128 v[196:199], v176 offset:57344
	ds_read_b128 v[200:203], v177 offset:49152
	ds_read_b128 v[204:207], v177 offset:57344
	ds_read_b128 v[208:211], v178 offset:49152
	ds_read_b128 v[212:215], v178 offset:57344
	ds_read_b128 v[216:219], v179 offset:49152
	ds_read_b128 v[220:223], v179 offset:57344
	v_add_f32_e32 v121, 0, v130
	v_add_f32_e32 v121, v134, v121
	s_waitcnt lgkmcnt(9)
	v_mfma_f32_32x32x16_bf16 v[48:63], v[32:35], v[84:87], 0
	v_add_f32_e32 v121, v131, v121
	v_add_f32_e32 v121, v135, v121
	v_add_f32_e32 v121, v132, v121
	v_add_f32_e32 v121, v185, v121
	v_add_f32_e32 v121, v133, v121
	v_add_f32_e32 v121, v186, v121
	v_add_f32_e32 v121, v122, v121
	v_add_f32_e32 v121, v125, v121
	s_waitcnt lgkmcnt(8)
	v_mfma_f32_32x32x16_bf16 v[32:47], v[36:39], v[84:87], 0
	v_add_f32_e32 v121, v123, v121
	v_add_f32_e32 v121, v126, v121
	v_exp_f32_e32 v116, v116
	v_add_f32_e32 v121, v124, v121
	v_exp_f32_e32 v117, v117
	v_add_f32_e32 v121, v127, v121
	s_waitcnt lgkmcnt(7)
	v_mfma_f32_32x32x16_bf16 v[48:63], v[192:195], v[80:83], v[48:63]
	v_exp_f32_e32 v114, v114
	v_add_f32_e32 v121, v128, v121
	v_exp_f32_e32 v115, v115
	v_add_f32_e32 v121, v129, v121
	v_exp_f32_e32 v110, v110
	s_waitcnt lgkmcnt(6)
	v_mfma_f32_32x32x16_bf16 v[32:47], v[196:199], v[80:83], v[32:47]
	v_add_f32_e32 v121, v116, v121
	v_exp_f32_e32 v111, v111
	v_add_f32_e32 v121, v117, v121
	v_exp_f32_e32 v106, v106
	v_add_f32_e32 v121, v114, v121
	s_waitcnt lgkmcnt(5)
	v_mfma_f32_32x32x16_bf16 v[48:63], v[200:203], v[76:79], v[48:63]
	ds_read_b128 v[224:227], v180 offset:49152
	ds_read_b128 v[228:231], v180 offset:57344
	v_exp_f32_e32 v107, v107
	v_add_f32_e32 v121, v115, v121
	v_exp_f32_e32 v104, v104
	v_add_f32_e32 v121, v110, v121
	v_exp_f32_e32 v105, v105
	s_waitcnt lgkmcnt(6)
	v_mfma_f32_32x32x16_bf16 v[32:47], v[204:207], v[76:79], v[32:47]
	v_add_f32_e32 v121, v111, v121
	v_exp_f32_e32 v118, v118
	v_add_f32_e32 v121, v106, v121
	v_exp_f32_e32 v119, v119
	v_add_f32_e32 v121, v107, v121
	s_waitcnt lgkmcnt(5)
	v_mfma_f32_32x32x16_bf16 v[48:63], v[208:211], v[72:75], v[48:63]
	v_exp_f32_e32 v112, v112
	v_add_f32_e32 v121, v104, v121
	v_exp_f32_e32 v113, v113
	v_add_f32_e32 v121, v105, v121
	v_exp_f32_e32 v108, v108
	s_waitcnt lgkmcnt(4)
	v_mfma_f32_32x32x16_bf16 v[32:47], v[212:215], v[72:75], v[32:47]
	v_add_f32_e32 v121, v118, v121
	v_exp_f32_e32 v109, v109
	v_add_f32_e32 v121, v119, v121
	v_add_f32_e32 v121, v112, v121
	v_add_f32_e32 v121, v113, v121
	v_add_f32_e32 v121, v108, v121
	v_add_f32_e32 v182, v109, v121
	s_waitcnt lgkmcnt(3)
	v_mfma_f32_32x32x16_bf16 v[48:63], v[216:219], v[68:71], v[48:63]
	v_mov_b32_e32 v183, v182
	v_cvt_pk_bf16_f32 v130, v130, v134
	v_cvt_pk_bf16_f32 v131, v131, v135
	v_cvt_pk_bf16_f32 v132, v132, v185
	v_cvt_pk_bf16_f32 v133, v133, v186
	v_cvt_pk_bf16_f32 v122, v122, v125
	v_cvt_pk_bf16_f32 v123, v123, v126
	v_cvt_pk_bf16_f32 v124, v124, v127
	s_waitcnt lgkmcnt(2)
	v_mfma_f32_32x32x16_bf16 v[32:47], v[220:223], v[68:71], v[32:47]
	v_cvt_pk_bf16_f32 v125, v128, v129
	v_cvt_pk_bf16_f32 v126, v116, v117
	v_cvt_pk_bf16_f32 v127, v114, v115
	v_cvt_pk_bf16_f32 v128, v110, v111
	v_cvt_pk_bf16_f32 v129, v106, v107
	v_cvt_pk_bf16_f32 v184, v104, v105
	v_cvt_pk_bf16_f32 v185, v118, v119
	v_cvt_pk_bf16_f32 v186, v112, v113
	s_waitcnt lgkmcnt(1)
	v_mfma_f32_32x32x16_bf16 v[48:63], v[224:227], v[64:67], v[48:63]
	v_permlane32_swap_b32_e32 v182, v183
	v_cvt_pk_bf16_f32 v187, v108, v109
	v_permlane32_swap_b32_e32 v184, v186
	v_permlane32_swap_b32_e32 v130, v132
	v_permlane32_swap_b32_e32 v131, v133
	v_permlane32_swap_b32_e32 v122, v124
	v_permlane32_swap_b32_e32 v123, v125
	v_permlane32_swap_b32_e32 v126, v128
	s_waitcnt lgkmcnt(0)
	v_mfma_f32_32x32x16_bf16 v[32:47], v[228:231], v[64:67], v[32:47]
	v_permlane32_swap_b32_e32 v127, v129
	v_permlane32_swap_b32_e32 v185, v187
	v_add_co_u32_e32 v104, vcc, s48, v154
	v_lshl_add_u64 v[112:113], v[150:151], 0, v[160:161]
	s_nop 0
	v_addc_co_u32_e32 v105, vcc, -1, v155, vcc
	v_add_co_u32_e32 v108, vcc, s49, v154
	v_lshl_add_u64 v[116:117], v[150:151], 0, v[158:159]
	s_nop 0
	v_addc_co_u32_e32 v109, vcc, -1, v155, vcc
	global_load_dwordx4 v[104:107], v[104:105], off
	s_nop 0
	global_load_dwordx4 v[108:111], v[108:109], off
	s_nop 0
	global_load_dwordx4 v[112:115], v[112:113], off
	s_nop 0
	global_load_dwordx4 v[116:119], v[116:117], off
	s_waitcnt vmcnt(4)
	ds_write_b128 v171, v[88:91] offset:32768
	ds_write_b128 v172, v[92:95] offset:32768
	ds_read_b64_tr_b16 v[192:193], v170 offset:0
	ds_read_b64_tr_b16 v[194:195], v170 offset:0x800
	ds_read_b64_tr_b16 v[196:197], v170 offset:0x1000
	ds_read_b64_tr_b16 v[198:199], v170 offset:0x1800
	ds_read_b64_tr_b16 v[200:201], v170 offset:0x2000
	ds_read_b64_tr_b16 v[202:203], v170 offset:0x2800
	ds_read_b64_tr_b16 v[204:205], v170 offset:0x3000
	ds_read_b64_tr_b16 v[206:207], v170 offset:0x3800
	s_waitcnt lgkmcnt(6)
	v_mfma_f32_32x32x16_bf16 v[0:15], v[130:133], v[192:195], v[0:15]
	ds_read_b64_tr_b16 v[192:193], v170 offset:0x200
	ds_read_b64_tr_b16 v[194:195], v170 offset:0xa00
	v_max_f32_e32 v121, v49, v49
	v_max_f32_e32 v134, v48, v48
	v_max_f32_e32 v121, v134, v121
	v_max3_f32 v121, v121, v50, v51
	v_max3_f32 v121, v121, v52, v53
	v_max3_f32 v121, v121, v54, v55
	v_max3_f32 v121, v121, v56, v57
	v_max3_f32 v121, v121, v58, v59
	v_max3_f32 v121, v121, v60, v61
	v_max3_f32 v121, v121, v62, v63
	v_max3_f32 v121, v121, v32, v33
	v_max3_f32 v121, v121, v34, v35
	s_waitcnt lgkmcnt(6)
; #define SWRITE(b, i) do { *(LAS bf16x8*)(V_lds + (b) * SHM_V + vst0) = sr_[i].vs0;          \
;     *(LAS bf16x8*)(V_lds + (b) * SHM_V + vst1) = sr_[i].vs1; const int kc = sc * 2;               \
;     *(LAS bf16x8*)(K_lds + (b) * SHM_K + KSWZ(sr, kc)) = sr_[i].ks0;                       \
;     *(LAS bf16x8*)(K_lds + (b) * SHM_K + KSWZ(32 + sr, kc)) = sr_[i].ks1; } while (0)
; #define SWAIT() asm volatile("s_waitcnt vmcnt(4)" ::: "memory")
; #define RESC(a) do { if (__any((a) < 1.f)) { if (hi == 0) al_l[r32] = (a); asm volatile("s_waitcnt lgkmcnt(0)" ::: "memory"); \
;     _Pragma("unroll") for (int d = 0; d < NDV; ++d) _Pragma("unroll") for (int r = 0; r < 16; ++r) o[d][r] *= al_l[crow(r, hi)]; } } while (0)
; template <int NDQ, int NDV> ...
;     ...
;     pv_d0<NDV>(o, vb0, pa0, pa1, pa2, pa3); partialSM(pB0, pB1, m_reg, mnB, alB, Cs, thr);
;     __syncthreads(); SWAIT(); SWRITE(0, SE);
;     RESC(alB); __syncthreads();
	v_mfma_f32_32x32x16_bf16 v[0:15], v[122:125], v[196:199], v[0:15]
	ds_read_b64_tr_b16 v[196:197], v170 offset:0x1200
	ds_read_b64_tr_b16 v[198:199], v170 offset:0x1a00
	v_max3_f32 v121, v121, v36, v37
	v_max3_f32 v121, v121, v38, v39
	v_max3_f32 v121, v121, v40, v41
	v_max3_f32 v121, v121, v42, v43
	v_max3_f32 v121, v121, v44, v45
	v_max3_f32 v121, v121, v46, v47
	v_mov_b32_e32 v134, v121
	s_nop 1
	v_permlane32_swap_b32_e32 v121, v134
	v_max_f32_e32 v134, v134, v134
	v_max_f32_e32 v121, v121, v121
	v_max_f32_e32 v121, v121, v134
	s_waitcnt lgkmcnt(6)
	v_mfma_f32_32x32x16_bf16 v[0:15], v[126:129], v[200:203], v[0:15]
	ds_read_b64_tr_b16 v[200:201], v170 offset:0x2200
	ds_read_b64_tr_b16 v[202:203], v170 offset:0x2a00
	ds_read_b64_tr_b16 v[208:209], v170 offset:0x3200
	ds_read_b64_tr_b16 v[210:211], v170 offset:0x3a00
	v_max_f32_e32 v252, v120, v120
	v_sub_f32_e32 v135, v121, v120
	v_max_f32_e32 v121, v252, v121
	v_sub_f32_e32 v252, v120, v121
	v_mul_f32_e32 v252, 0x3e16c740, v252
	v_exp_f32_e32 v252, v252
	v_cmp_ge_f32_e32 vcc, s46, v135
	s_cmp_eq_u64 vcc, exec
	s_cselect_b64 s[6:7], -1, 0
	v_cndmask_b32_e64 v253, v121, v120, s[6:7]
	v_mul_f32_e32 v251, 0xbe16c740, v253
	s_waitcnt lgkmcnt(8)
	v_mfma_f32_32x32x16_bf16 v[0:15], v[184:187], v[204:207], v[0:15]
	v_fmamk_f32 v48, v48, 0x3e16c740, v251
	v_fmamk_f32 v49, v49, 0x3e16c740, v251
	v_fmamk_f32 v50, v50, 0x3e16c740, v251
	v_fmamk_f32 v51, v51, 0x3e16c740, v251
	v_fmamk_f32 v52, v52, 0x3e16c740, v251
	v_fmamk_f32 v53, v53, 0x3e16c740, v251
	v_fmamk_f32 v54, v54, 0x3e16c740, v251
	v_fmamk_f32 v55, v55, 0x3e16c740, v251
	v_fmamk_f32 v56, v56, 0x3e16c740, v251
	v_fmamk_f32 v57, v57, 0x3e16c740, v251
	v_fmamk_f32 v58, v58, 0x3e16c740, v251
	v_fmamk_f32 v59, v59, 0x3e16c740, v251
	s_waitcnt lgkmcnt(6)
	v_mfma_f32_32x32x16_bf16 v[16:31], v[130:133], v[192:195], v[16:31]
	v_fmamk_f32 v60, v60, 0x3e16c740, v251
	v_fmamk_f32 v61, v61, 0x3e16c740, v251
	v_fmamk_f32 v62, v62, 0x3e16c740, v251
	v_fmamk_f32 v63, v63, 0x3e16c740, v251
	v_exp_f32_e32 v120, v48
	v_exp_f32_e32 v135, v49
	v_exp_f32_e32 v121, v50
	v_exp_f32_e32 v134, v51
	v_exp_f32_e32 v133, v53
	v_exp_f32_e32 v132, v55
	s_waitcnt lgkmcnt(4)
	v_mfma_f32_32x32x16_bf16 v[16:31], v[122:125], v[196:199], v[16:31]
	v_exp_f32_e32 v131, v57
	v_exp_f32_e32 v130, v59
	v_exp_f32_e32 v122, v52
	v_exp_f32_e32 v123, v54
	v_exp_f32_e32 v124, v56
	v_exp_f32_e32 v125, v58
	s_waitcnt lgkmcnt(2)
	v_mfma_f32_32x32x16_bf16 v[16:31], v[126:129], v[200:203], v[16:31]
	v_exp_f32_e32 v126, v60
	v_exp_f32_e32 v129, v61
	v_exp_f32_e32 v127, v62
	v_exp_f32_e32 v128, v63
	s_waitcnt lgkmcnt(0)
	v_mfma_f32_32x32x16_bf16 v[16:31], v[184:187], v[208:211], v[16:31]
	s_barrier
	s_waitcnt vmcnt(4)
	v_cndmask_b32_e64 v184, v252, 1.0, s[6:7]
	v_cmp_gt_f32_e32 vcc, 1.0, v184
	s_waitcnt vmcnt(4)
	ds_write_b128 v173, v[96:99]
	ds_write_b128 v174, v[100:103]
	s_cbranch_vccz .LBB0_1492
	s_and_saveexec_b64 s[10:11], s[4:5]
	ds_write_b32 v167, v184 offset:128
	s_or_b64 exec, exec, s[10:11]
	s_waitcnt lgkmcnt(0)
	v_add_u32_e32 v134, v149, v146
	ds_read_b128 v[122:125], v134 offset:224
	ds_read_b128 v[126:129], v134 offset:192
	ds_read_b128 v[130:133], v134 offset:160
	ds_read_b128 v[186:189], v134 offset:128
	s_waitcnt lgkmcnt(3)
	v_pk_mul_f32 v[12:13], v[12:13], v[122:123]
	s_waitcnt lgkmcnt(2)
	v_pk_mul_f32 v[8:9], v[8:9], v[126:127]
	s_waitcnt lgkmcnt(1)
	v_pk_mul_f32 v[4:5], v[4:5], v[130:131]
	v_pk_mul_f32 v[14:15], v[14:15], v[124:125]
	v_pk_mul_f32 v[10:11], v[10:11], v[128:129]
	v_pk_mul_f32 v[6:7], v[6:7], v[132:133]
	s_waitcnt lgkmcnt(0)
	v_pk_mul_f32 v[2:3], v[2:3], v[188:189]
	v_pk_mul_f32 v[0:1], v[0:1], v[186:187]
	v_pk_mul_f32 v[28:29], v[28:29], v[122:123]
	v_pk_mul_f32 v[24:25], v[24:25], v[126:127]
	v_pk_mul_f32 v[20:21], v[20:21], v[130:131]
	v_pk_mul_f32 v[30:31], v[30:31], v[124:125]
	v_pk_mul_f32 v[26:27], v[26:27], v[128:129]
	v_pk_mul_f32 v[22:23], v[22:23], v[132:133]
	v_pk_mul_f32 v[18:19], v[18:19], v[188:189]
	v_pk_mul_f32 v[16:17], v[16:17], v[186:187]
; #define SBAR() __builtin_amdgcn_sched_barrier(0)
; #define SLOAD(i, k0) do { sr_[i].vs0 = *reinterpret_cast<const bf16x8*>(vptr + (size_t)((k0) + sr) * vstr); \
;     sr_[i].vs1 = *reinterpret_cast<const bf16x8*>(vptr + (size_t)((k0) + 32 + sr) * vstr); \
;     sr_[i].ks0 = *reinterpret_cast<const bf16x8*>(kptr + (size_t)((k0) + sr) * kstr); \
;     sr_[i].ks1 = *reinterpret_cast<const bf16x8*>(kptr + (size_t)((k0) + 32 + sr) * kstr); } while (0)
; template <int NDQ, int NDV> ...
;     ...
;     SBAR(); qkt<NDQ>(pA0, pA1, K_lds, qr, r32, hi);
;     finishSM(pB0, pB1, alB, l_reg, pa0, pa1, pa2, pa3); SBAR();
;     if (j + 3 < NT) SLOAD(SE, (j + 3) * 64); SBAR();
.LBB0_1492:
	v_mov_b32_e32 v185, v253
	v_fmamk_f32 v187, v38, 0x3e16c740, v251
	v_fmamk_f32 v188, v39, 0x3e16c740, v251
	v_fmamk_f32 v195, v32, 0x3e16c740, v251
	v_fmamk_f32 v196, v33, 0x3e16c740, v251
	v_fmamk_f32 v197, v34, 0x3e16c740, v251
	v_fmamk_f32 v198, v35, 0x3e16c740, v251
	v_fmamk_f32 v199, v36, 0x3e16c740, v251
	v_fmamk_f32 v200, v37, 0x3e16c740, v251
	v_fmamk_f32 v189, v40, 0x3e16c740, v251
	v_fmamk_f32 v191, v41, 0x3e16c740, v251
	v_fmamk_f32 v192, v42, 0x3e16c740, v251
	v_fmamk_f32 v193, v43, 0x3e16c740, v251
	v_fmamk_f32 v194, v44, 0x3e16c740, v251
	v_fmamk_f32 v201, v45, 0x3e16c740, v251
	v_fmamk_f32 v202, v46, 0x3e16c740, v251
	v_fmamk_f32 v186, v47, 0x3e16c740, v251
	ds_read_b128 v[32:35], v175 offset:32768
	ds_read_b128 v[36:39], v175 offset:40960
	ds_read_b128 v[204:207], v176 offset:32768
	ds_read_b128 v[208:211], v176 offset:40960
	ds_read_b128 v[212:215], v177 offset:32768
	ds_read_b128 v[216:219], v177 offset:40960
	ds_read_b128 v[220:223], v178 offset:32768
	ds_read_b128 v[224:227], v178 offset:40960
	ds_read_b128 v[228:231], v179 offset:32768
	ds_read_b128 v[232:235], v179 offset:40960
	v_exp_f32_e32 v203, v187
	v_add_f32_e32 v187, 0, v120
	s_waitcnt lgkmcnt(9)
	v_mfma_f32_32x32x16_bf16 v[48:63], v[32:35], v[84:87], 0
	v_add_f32_e32 v187, v135, v187
	v_add_f32_e32 v187, v121, v187
	v_add_f32_e32 v187, v134, v187
	v_add_f32_e32 v187, v122, v187
	v_add_f32_e32 v187, v133, v187
	v_add_f32_e32 v187, v123, v187
	v_add_f32_e32 v187, v132, v187
	v_add_f32_e32 v187, v124, v187
	s_waitcnt lgkmcnt(8)
	v_mfma_f32_32x32x16_bf16 v[32:47], v[36:39], v[84:87], 0
	v_add_f32_e32 v187, v131, v187
	v_add_f32_e32 v187, v125, v187
	v_add_f32_e32 v187, v130, v187
	v_exp_f32_e32 v195, v195
	v_add_f32_e32 v187, v126, v187
	v_exp_f32_e32 v196, v196
	s_waitcnt lgkmcnt(7)
	v_mfma_f32_32x32x16_bf16 v[48:63], v[204:207], v[80:83], v[48:63]
	v_add_f32_e32 v187, v129, v187
	v_exp_f32_e32 v197, v197
	v_add_f32_e32 v187, v127, v187
	v_exp_f32_e32 v198, v198
	v_add_f32_e32 v187, v128, v187
	s_waitcnt lgkmcnt(6)
	v_mfma_f32_32x32x16_bf16 v[32:47], v[208:211], v[80:83], v[32:47]
	v_exp_f32_e32 v199, v199
	v_add_f32_e32 v187, v195, v187
	v_exp_f32_e32 v200, v200
	v_add_f32_e32 v187, v196, v187
	v_add_f32_e32 v187, v197, v187
	s_waitcnt lgkmcnt(5)
	v_mfma_f32_32x32x16_bf16 v[48:63], v[212:215], v[76:79], v[48:63]
	ds_read_b128 v[236:239], v180 offset:32768
	ds_read_b128 v[240:243], v180 offset:40960
	v_exp_f32_e32 v204, v188
	v_add_f32_e32 v187, v198, v187
	v_exp_f32_e32 v189, v189
	v_add_f32_e32 v187, v199, v187
	v_exp_f32_e32 v191, v191
	s_waitcnt lgkmcnt(6)
	v_mfma_f32_32x32x16_bf16 v[32:47], v[216:219], v[76:79], v[32:47]
	v_add_f32_e32 v187, v200, v187
	v_exp_f32_e32 v192, v192
	v_add_f32_e32 v187, v203, v187
	v_exp_f32_e32 v193, v193
	v_add_f32_e32 v187, v204, v187
	s_waitcnt lgkmcnt(5)
	v_mfma_f32_32x32x16_bf16 v[48:63], v[220:223], v[72:75], v[48:63]
	v_exp_f32_e32 v194, v194
	v_add_f32_e32 v187, v189, v187
	v_exp_f32_e32 v201, v201
	v_add_f32_e32 v187, v191, v187
	v_exp_f32_e32 v202, v202
	s_waitcnt lgkmcnt(4)
	v_mfma_f32_32x32x16_bf16 v[32:47], v[224:227], v[72:75], v[32:47]
	v_add_f32_e32 v187, v192, v187
	v_exp_f32_e32 v186, v186
	v_add_f32_e32 v187, v193, v187
	v_add_f32_e32 v187, v194, v187
	v_add_f32_e32 v187, v201, v187
	v_add_f32_e32 v187, v202, v187
	v_add_f32_e32 v187, v186, v187
	s_waitcnt lgkmcnt(3)
	v_mfma_f32_32x32x16_bf16 v[48:63], v[228:231], v[68:71], v[48:63]
	v_mov_b32_e32 v188, v187
	v_cvt_pk_bf16_f32 v120, v120, v135
	v_cvt_pk_bf16_f32 v121, v121, v134
	v_cvt_pk_bf16_f32 v122, v122, v133
	v_cvt_pk_bf16_f32 v123, v123, v132
	v_cvt_pk_bf16_f32 v124, v124, v131
	v_cvt_pk_bf16_f32 v125, v125, v130
	v_cvt_pk_bf16_f32 v126, v126, v129
	s_waitcnt lgkmcnt(2)
	v_mfma_f32_32x32x16_bf16 v[32:47], v[232:235], v[68:71], v[32:47]
	v_cvt_pk_bf16_f32 v127, v127, v128
	v_cvt_pk_bf16_f32 v132, v195, v196
	v_cvt_pk_bf16_f32 v133, v197, v198
	v_cvt_pk_bf16_f32 v134, v199, v200
	v_cvt_pk_bf16_f32 v135, v203, v204
	v_cvt_pk_bf16_f32 v128, v189, v191
	v_cvt_pk_bf16_f32 v129, v192, v193
	v_cvt_pk_bf16_f32 v130, v194, v201
	s_waitcnt lgkmcnt(1)
	v_mfma_f32_32x32x16_bf16 v[48:63], v[236:239], v[64:67], v[48:63]
	v_cvt_pk_bf16_f32 v131, v202, v186
	v_permlane32_swap_b32_e32 v187, v188
	v_permlane32_swap_b32_e32 v120, v122
	v_permlane32_swap_b32_e32 v121, v123
	v_permlane32_swap_b32_e32 v124, v126
	v_permlane32_swap_b32_e32 v125, v127
	v_permlane32_swap_b32_e32 v132, v134
	v_permlane32_swap_b32_e32 v133, v135
	s_waitcnt lgkmcnt(0)
	v_mfma_f32_32x32x16_bf16 v[32:47], v[240:243], v[64:67], v[32:47]
	v_permlane32_swap_b32_e32 v128, v130
	v_permlane32_swap_b32_e32 v129, v131
	s_cmp_ge_u32 s57, s56
	s_cselect_b64 s[10:11], -1, 0
	s_and_b64 vcc, exec, s[10:11]
	s_cbranch_vccnz .LBB0_1494
	v_add_co_u32_e32 v88, vcc, 0xffff0000, v154
	v_lshl_add_u64 v[92:93], v[150:151], 0, v[152:153]
	s_nop 0
	v_addc_co_u32_e32 v89, vcc, -1, v155, vcc
	global_load_dwordx4 v[96:99], v[88:89], off
	global_load_dwordx4 v[100:103], v[154:155], off
	v_lshl_add_u64 v[88:89], v[150:151], 0, v[156:157]
	global_load_dwordx4 v[88:91], v[88:89], off
	s_nop 0
	global_load_dwordx4 v[92:95], v[92:93], off
